# v52 = v51 + mod_item SiLU staging loop fully unrolled: all 34 loads of a thread issued first, then the SiLU bodies behind counted waits
# speedup vs baseline: 1.0171x; 1.0061x over previous
.LBB0_139:
	s_barrier
	s_and_saveexec_b64 s[6:7], s[4:5]
	s_cbranch_execz .LBB0_146
	v_add_u32_e32 v214, s76, v139
	v_lshlrev_b32_e32 v214, 2, v214
	global_load_dword v180, v214, s[38:39]
	v_add_u32_e32 v215, 0x400, v214
	global_load_dword v181, v215, s[38:39]
	v_add_u32_e32 v215, 0x1000, v214
	global_load_dword v182, v215, s[38:39]
	v_add_u32_e32 v215, 0x1400, v214
	global_load_dword v183, v215, s[38:39]
	v_add_u32_e32 v215, 0x2000, v214
	global_load_dword v184, v215, s[38:39]
	v_add_u32_e32 v215, 0x2400, v214
	global_load_dword v185, v215, s[38:39]
	v_add_u32_e32 v215, 0x3000, v214
	global_load_dword v186, v215, s[38:39]
	v_add_u32_e32 v215, 0x3400, v214
	global_load_dword v187, v215, s[38:39]
	v_add_u32_e32 v215, 0x4000, v214
	global_load_dword v188, v215, s[38:39]
	v_add_u32_e32 v215, 0x4400, v214
	global_load_dword v189, v215, s[38:39]
	v_add_u32_e32 v215, 0x5000, v214
	global_load_dword v190, v215, s[38:39]
	v_add_u32_e32 v215, 0x5400, v214
	global_load_dword v191, v215, s[38:39]
	v_add_u32_e32 v215, 0x6000, v214
	global_load_dword v192, v215, s[38:39]
	v_add_u32_e32 v215, 0x6400, v214
	global_load_dword v193, v215, s[38:39]
	v_add_u32_e32 v215, 0x7000, v214
	global_load_dword v194, v215, s[38:39]
	v_add_u32_e32 v215, 0x7400, v214
	global_load_dword v195, v215, s[38:39]
	v_add_u32_e32 v215, 0x8000, v214
	global_load_dword v196, v215, s[38:39]
	v_add_u32_e32 v215, 0x8400, v214
	global_load_dword v197, v215, s[38:39]
	v_add_u32_e32 v215, 0x9000, v214
	global_load_dword v198, v215, s[38:39]
	v_add_u32_e32 v215, 0x9400, v214
	global_load_dword v199, v215, s[38:39]
	v_add_u32_e32 v215, 0xa000, v214
	global_load_dword v200, v215, s[38:39]
	v_add_u32_e32 v215, 0xa400, v214
	global_load_dword v201, v215, s[38:39]
	v_add_u32_e32 v215, 0xb000, v214
	global_load_dword v202, v215, s[38:39]
	v_add_u32_e32 v215, 0xb400, v214
	global_load_dword v203, v215, s[38:39]
	v_add_u32_e32 v215, 0xc000, v214
	global_load_dword v204, v215, s[38:39]
	v_add_u32_e32 v215, 0xc400, v214
	global_load_dword v205, v215, s[38:39]
	v_add_u32_e32 v215, 0xd000, v214
	global_load_dword v206, v215, s[38:39]
	v_add_u32_e32 v215, 0xd400, v214
	global_load_dword v207, v215, s[38:39]
	v_add_u32_e32 v215, 0xe000, v214
	global_load_dword v208, v215, s[38:39]
	v_add_u32_e32 v215, 0xe400, v214
	global_load_dword v209, v215, s[38:39]
	v_add_u32_e32 v215, 0xf000, v214
	global_load_dword v210, v215, s[38:39]
	v_add_u32_e32 v215, 0xf400, v214
	global_load_dword v211, v215, s[38:39]
	global_load_dword v212, v214, s[42:43]
	v_add_u32_e32 v215, 0x400, v214
	global_load_dword v213, v215, s[42:43]
	s_waitcnt vmcnt(33)
	v_mov_b32_e32 v0, v180
	v_mul_f32_e32 v1, 0xbfb8aa3b, v0
	v_exp_f32_e32 v1, v1
	s_nop 0
	v_add_f32_e32 v1, 1.0, v1
	v_div_scale_f32 v4, s[72:73], v1, v1, 1.0
	v_rcp_f32_e32 v5, v4
	s_nop 0
	v_fma_f32 v6, -v4, v5, 1.0
	v_fmac_f32_e32 v5, v6, v5
	v_div_scale_f32 v6, vcc, 1.0, v1, 1.0
	v_mul_f32_e32 v7, v6, v5
	v_fma_f32 v10, -v4, v7, v6
	v_fmac_f32_e32 v7, v10, v5
	v_fma_f32 v4, -v4, v7, v6
	v_div_fmas_f32 v4, v4, v5, v7
	v_div_fixup_f32 v1, v4, v1, 1.0
	v_mul_f32_e32 v0, v0, v1
	ds_write_b32 v140, v0
	s_waitcnt vmcnt(32)
	v_mov_b32_e32 v0, v181
	v_mul_f32_e32 v1, 0xbfb8aa3b, v0
	v_exp_f32_e32 v1, v1
	s_nop 0
	v_add_f32_e32 v1, 1.0, v1
	v_div_scale_f32 v4, s[72:73], v1, v1, 1.0
	v_rcp_f32_e32 v5, v4
	s_nop 0
	v_fma_f32 v6, -v4, v5, 1.0
	v_fmac_f32_e32 v5, v6, v5
	v_div_scale_f32 v6, vcc, 1.0, v1, 1.0
	v_mul_f32_e32 v7, v6, v5
	v_fma_f32 v10, -v4, v7, v6
	v_fmac_f32_e32 v7, v10, v5
	v_fma_f32 v4, -v4, v7, v6
	v_div_fmas_f32 v4, v4, v5, v7
	v_div_fixup_f32 v1, v4, v1, 1.0
	v_mul_f32_e32 v0, v0, v1
	ds_write_b32 v140, v0 offset:1024
	s_waitcnt vmcnt(31)
	v_mov_b32_e32 v0, v182
	v_mul_f32_e32 v1, 0xbfb8aa3b, v0
	v_exp_f32_e32 v1, v1
	s_nop 0
	v_add_f32_e32 v1, 1.0, v1
	v_div_scale_f32 v4, s[72:73], v1, v1, 1.0
	v_rcp_f32_e32 v5, v4
	s_nop 0
	v_fma_f32 v6, -v4, v5, 1.0
	v_fmac_f32_e32 v5, v6, v5
	v_div_scale_f32 v6, vcc, 1.0, v1, 1.0
	v_mul_f32_e32 v7, v6, v5
	v_fma_f32 v10, -v4, v7, v6
	v_fmac_f32_e32 v7, v10, v5
	v_fma_f32 v4, -v4, v7, v6
	v_div_fmas_f32 v4, v4, v5, v7
	v_div_fixup_f32 v1, v4, v1, 1.0
	v_mul_f32_e32 v0, v0, v1
	ds_write_b32 v140, v0 offset:2048
	s_waitcnt vmcnt(30)
	v_mov_b32_e32 v0, v183
	v_mul_f32_e32 v1, 0xbfb8aa3b, v0
	v_exp_f32_e32 v1, v1
	s_nop 0
	v_add_f32_e32 v1, 1.0, v1
	v_div_scale_f32 v4, s[72:73], v1, v1, 1.0
	v_rcp_f32_e32 v5, v4
	s_nop 0
	v_fma_f32 v6, -v4, v5, 1.0
	v_fmac_f32_e32 v5, v6, v5
	v_div_scale_f32 v6, vcc, 1.0, v1, 1.0
	v_mul_f32_e32 v7, v6, v5
	v_fma_f32 v10, -v4, v7, v6
	v_fmac_f32_e32 v7, v10, v5
	v_fma_f32 v4, -v4, v7, v6
	v_div_fmas_f32 v4, v4, v5, v7
	v_div_fixup_f32 v1, v4, v1, 1.0
	v_mul_f32_e32 v0, v0, v1
	ds_write_b32 v140, v0 offset:3072
	s_waitcnt vmcnt(29)
	v_mov_b32_e32 v0, v184
	v_mul_f32_e32 v1, 0xbfb8aa3b, v0
	v_exp_f32_e32 v1, v1
	s_nop 0
	v_add_f32_e32 v1, 1.0, v1
	v_div_scale_f32 v4, s[72:73], v1, v1, 1.0
	v_rcp_f32_e32 v5, v4
	s_nop 0
	v_fma_f32 v6, -v4, v5, 1.0
	v_fmac_f32_e32 v5, v6, v5
	v_div_scale_f32 v6, vcc, 1.0, v1, 1.0
	v_mul_f32_e32 v7, v6, v5
	v_fma_f32 v10, -v4, v7, v6
	v_fmac_f32_e32 v7, v10, v5
	v_fma_f32 v4, -v4, v7, v6
	v_div_fmas_f32 v4, v4, v5, v7
	v_div_fixup_f32 v1, v4, v1, 1.0
	v_mul_f32_e32 v0, v0, v1
	ds_write_b32 v140, v0 offset:4096
	s_waitcnt vmcnt(28)
	v_mov_b32_e32 v0, v185
	v_mul_f32_e32 v1, 0xbfb8aa3b, v0
	v_exp_f32_e32 v1, v1
	s_nop 0
	v_add_f32_e32 v1, 1.0, v1
	v_div_scale_f32 v4, s[72:73], v1, v1, 1.0
	v_rcp_f32_e32 v5, v4
	s_nop 0
	v_fma_f32 v6, -v4, v5, 1.0
	v_fmac_f32_e32 v5, v6, v5
	v_div_scale_f32 v6, vcc, 1.0, v1, 1.0
	v_mul_f32_e32 v7, v6, v5
	v_fma_f32 v10, -v4, v7, v6
	v_fmac_f32_e32 v7, v10, v5
	v_fma_f32 v4, -v4, v7, v6
	v_div_fmas_f32 v4, v4, v5, v7
	v_div_fixup_f32 v1, v4, v1, 1.0
	v_mul_f32_e32 v0, v0, v1
	ds_write_b32 v140, v0 offset:5120
	s_waitcnt vmcnt(27)
	v_mov_b32_e32 v0, v186
	v_mul_f32_e32 v1, 0xbfb8aa3b, v0
	v_exp_f32_e32 v1, v1
	s_nop 0
	v_add_f32_e32 v1, 1.0, v1
	v_div_scale_f32 v4, s[72:73], v1, v1, 1.0
	v_rcp_f32_e32 v5, v4
	s_nop 0
	v_fma_f32 v6, -v4, v5, 1.0
	v_fmac_f32_e32 v5, v6, v5
	v_div_scale_f32 v6, vcc, 1.0, v1, 1.0
	v_mul_f32_e32 v7, v6, v5
	v_fma_f32 v10, -v4, v7, v6
	v_fmac_f32_e32 v7, v10, v5
	v_fma_f32 v4, -v4, v7, v6
	v_div_fmas_f32 v4, v4, v5, v7
	v_div_fixup_f32 v1, v4, v1, 1.0
	v_mul_f32_e32 v0, v0, v1
	ds_write_b32 v140, v0 offset:6144
	s_waitcnt vmcnt(26)
	v_mov_b32_e32 v0, v187
	v_mul_f32_e32 v1, 0xbfb8aa3b, v0
	v_exp_f32_e32 v1, v1
	s_nop 0
	v_add_f32_e32 v1, 1.0, v1
	v_div_scale_f32 v4, s[72:73], v1, v1, 1.0
	v_rcp_f32_e32 v5, v4
	s_nop 0
	v_fma_f32 v6, -v4, v5, 1.0
	v_fmac_f32_e32 v5, v6, v5
	v_div_scale_f32 v6, vcc, 1.0, v1, 1.0
	v_mul_f32_e32 v7, v6, v5
	v_fma_f32 v10, -v4, v7, v6
	v_fmac_f32_e32 v7, v10, v5
	v_fma_f32 v4, -v4, v7, v6
	v_div_fmas_f32 v4, v4, v5, v7
	v_div_fixup_f32 v1, v4, v1, 1.0
	v_mul_f32_e32 v0, v0, v1
	ds_write_b32 v140, v0 offset:7168
	s_waitcnt vmcnt(25)
	v_mov_b32_e32 v0, v188
	v_mul_f32_e32 v1, 0xbfb8aa3b, v0
	v_exp_f32_e32 v1, v1
	s_nop 0
	v_add_f32_e32 v1, 1.0, v1
	v_div_scale_f32 v4, s[72:73], v1, v1, 1.0
	v_rcp_f32_e32 v5, v4
	s_nop 0
	v_fma_f32 v6, -v4, v5, 1.0
	v_fmac_f32_e32 v5, v6, v5
	v_div_scale_f32 v6, vcc, 1.0, v1, 1.0
	v_mul_f32_e32 v7, v6, v5
	v_fma_f32 v10, -v4, v7, v6
	v_fmac_f32_e32 v7, v10, v5
	v_fma_f32 v4, -v4, v7, v6
	v_div_fmas_f32 v4, v4, v5, v7
	v_div_fixup_f32 v1, v4, v1, 1.0
	v_mul_f32_e32 v0, v0, v1
	ds_write_b32 v140, v0 offset:8192
	s_waitcnt vmcnt(24)
	v_mov_b32_e32 v0, v189
	v_mul_f32_e32 v1, 0xbfb8aa3b, v0
	v_exp_f32_e32 v1, v1
	s_nop 0
	v_add_f32_e32 v1, 1.0, v1
	v_div_scale_f32 v4, s[72:73], v1, v1, 1.0
	v_rcp_f32_e32 v5, v4
	s_nop 0
	v_fma_f32 v6, -v4, v5, 1.0
	v_fmac_f32_e32 v5, v6, v5
	v_div_scale_f32 v6, vcc, 1.0, v1, 1.0
	v_mul_f32_e32 v7, v6, v5
	v_fma_f32 v10, -v4, v7, v6
	v_fmac_f32_e32 v7, v10, v5
	v_fma_f32 v4, -v4, v7, v6
	v_div_fmas_f32 v4, v4, v5, v7
	v_div_fixup_f32 v1, v4, v1, 1.0
	v_mul_f32_e32 v0, v0, v1
	ds_write_b32 v140, v0 offset:9216
	s_waitcnt vmcnt(23)
	v_mov_b32_e32 v0, v190
	v_mul_f32_e32 v1, 0xbfb8aa3b, v0
	v_exp_f32_e32 v1, v1
	s_nop 0
	v_add_f32_e32 v1, 1.0, v1
	v_div_scale_f32 v4, s[72:73], v1, v1, 1.0
	v_rcp_f32_e32 v5, v4
	s_nop 0
	v_fma_f32 v6, -v4, v5, 1.0
	v_fmac_f32_e32 v5, v6, v5
	v_div_scale_f32 v6, vcc, 1.0, v1, 1.0
	v_mul_f32_e32 v7, v6, v5
	v_fma_f32 v10, -v4, v7, v6
	v_fmac_f32_e32 v7, v10, v5
	v_fma_f32 v4, -v4, v7, v6
	v_div_fmas_f32 v4, v4, v5, v7
	v_div_fixup_f32 v1, v4, v1, 1.0
	v_mul_f32_e32 v0, v0, v1
	ds_write_b32 v140, v0 offset:10240
	s_waitcnt vmcnt(22)
	v_mov_b32_e32 v0, v191
	v_mul_f32_e32 v1, 0xbfb8aa3b, v0
	v_exp_f32_e32 v1, v1
	s_nop 0
	v_add_f32_e32 v1, 1.0, v1
	v_div_scale_f32 v4, s[72:73], v1, v1, 1.0
	v_rcp_f32_e32 v5, v4
	s_nop 0
	v_fma_f32 v6, -v4, v5, 1.0
	v_fmac_f32_e32 v5, v6, v5
	v_div_scale_f32 v6, vcc, 1.0, v1, 1.0
	v_mul_f32_e32 v7, v6, v5
	v_fma_f32 v10, -v4, v7, v6
	v_fmac_f32_e32 v7, v10, v5
	v_fma_f32 v4, -v4, v7, v6
	v_div_fmas_f32 v4, v4, v5, v7
	v_div_fixup_f32 v1, v4, v1, 1.0
	v_mul_f32_e32 v0, v0, v1
	ds_write_b32 v140, v0 offset:11264
	s_waitcnt vmcnt(21)
	v_mov_b32_e32 v0, v192
	v_mul_f32_e32 v1, 0xbfb8aa3b, v0
	v_exp_f32_e32 v1, v1
	s_nop 0
	v_add_f32_e32 v1, 1.0, v1
	v_div_scale_f32 v4, s[72:73], v1, v1, 1.0
	v_rcp_f32_e32 v5, v4
	s_nop 0
	v_fma_f32 v6, -v4, v5, 1.0
	v_fmac_f32_e32 v5, v6, v5
	v_div_scale_f32 v6, vcc, 1.0, v1, 1.0
	v_mul_f32_e32 v7, v6, v5
	v_fma_f32 v10, -v4, v7, v6
	v_fmac_f32_e32 v7, v10, v5
	v_fma_f32 v4, -v4, v7, v6
	v_div_fmas_f32 v4, v4, v5, v7
	v_div_fixup_f32 v1, v4, v1, 1.0
	v_mul_f32_e32 v0, v0, v1
	ds_write_b32 v140, v0 offset:12288
	s_waitcnt vmcnt(20)
	v_mov_b32_e32 v0, v193
	v_mul_f32_e32 v1, 0xbfb8aa3b, v0
	v_exp_f32_e32 v1, v1
	s_nop 0
	v_add_f32_e32 v1, 1.0, v1
	v_div_scale_f32 v4, s[72:73], v1, v1, 1.0
	v_rcp_f32_e32 v5, v4
	s_nop 0
	v_fma_f32 v6, -v4, v5, 1.0
	v_fmac_f32_e32 v5, v6, v5
	v_div_scale_f32 v6, vcc, 1.0, v1, 1.0
	v_mul_f32_e32 v7, v6, v5
	v_fma_f32 v10, -v4, v7, v6
	v_fmac_f32_e32 v7, v10, v5
	v_fma_f32 v4, -v4, v7, v6
	v_div_fmas_f32 v4, v4, v5, v7
	v_div_fixup_f32 v1, v4, v1, 1.0
	v_mul_f32_e32 v0, v0, v1
	ds_write_b32 v140, v0 offset:13312
	s_waitcnt vmcnt(19)
	v_mov_b32_e32 v0, v194
	v_mul_f32_e32 v1, 0xbfb8aa3b, v0
	v_exp_f32_e32 v1, v1
	s_nop 0
	v_add_f32_e32 v1, 1.0, v1
	v_div_scale_f32 v4, s[72:73], v1, v1, 1.0
	v_rcp_f32_e32 v5, v4
	s_nop 0
	v_fma_f32 v6, -v4, v5, 1.0
	v_fmac_f32_e32 v5, v6, v5
	v_div_scale_f32 v6, vcc, 1.0, v1, 1.0
	v_mul_f32_e32 v7, v6, v5
	v_fma_f32 v10, -v4, v7, v6
	v_fmac_f32_e32 v7, v10, v5
	v_fma_f32 v4, -v4, v7, v6
	v_div_fmas_f32 v4, v4, v5, v7
	v_div_fixup_f32 v1, v4, v1, 1.0
	v_mul_f32_e32 v0, v0, v1
	ds_write_b32 v140, v0 offset:14336
	s_waitcnt vmcnt(18)
	v_mov_b32_e32 v0, v195
	v_mul_f32_e32 v1, 0xbfb8aa3b, v0
	v_exp_f32_e32 v1, v1
	s_nop 0
	v_add_f32_e32 v1, 1.0, v1
	v_div_scale_f32 v4, s[72:73], v1, v1, 1.0
	v_rcp_f32_e32 v5, v4
	s_nop 0
	v_fma_f32 v6, -v4, v5, 1.0
	v_fmac_f32_e32 v5, v6, v5
	v_div_scale_f32 v6, vcc, 1.0, v1, 1.0
	v_mul_f32_e32 v7, v6, v5
	v_fma_f32 v10, -v4, v7, v6
	v_fmac_f32_e32 v7, v10, v5
	v_fma_f32 v4, -v4, v7, v6
	v_div_fmas_f32 v4, v4, v5, v7
	v_div_fixup_f32 v1, v4, v1, 1.0
	v_mul_f32_e32 v0, v0, v1
	ds_write_b32 v140, v0 offset:15360
	s_waitcnt vmcnt(17)
	v_mov_b32_e32 v0, v196
	v_mul_f32_e32 v1, 0xbfb8aa3b, v0
	v_exp_f32_e32 v1, v1
	s_nop 0
	v_add_f32_e32 v1, 1.0, v1
	v_div_scale_f32 v4, s[72:73], v1, v1, 1.0
	v_rcp_f32_e32 v5, v4
	s_nop 0
	v_fma_f32 v6, -v4, v5, 1.0
	v_fmac_f32_e32 v5, v6, v5
	v_div_scale_f32 v6, vcc, 1.0, v1, 1.0
	v_mul_f32_e32 v7, v6, v5
	v_fma_f32 v10, -v4, v7, v6
	v_fmac_f32_e32 v7, v10, v5
	v_fma_f32 v4, -v4, v7, v6
	v_div_fmas_f32 v4, v4, v5, v7
	v_div_fixup_f32 v1, v4, v1, 1.0
	v_mul_f32_e32 v0, v0, v1
	ds_write_b32 v140, v0 offset:16384
	s_waitcnt vmcnt(16)
	v_mov_b32_e32 v0, v197
	v_mul_f32_e32 v1, 0xbfb8aa3b, v0
	v_exp_f32_e32 v1, v1
	s_nop 0
	v_add_f32_e32 v1, 1.0, v1
	v_div_scale_f32 v4, s[72:73], v1, v1, 1.0
	v_rcp_f32_e32 v5, v4
	s_nop 0
	v_fma_f32 v6, -v4, v5, 1.0
	v_fmac_f32_e32 v5, v6, v5
	v_div_scale_f32 v6, vcc, 1.0, v1, 1.0
	v_mul_f32_e32 v7, v6, v5
	v_fma_f32 v10, -v4, v7, v6
	v_fmac_f32_e32 v7, v10, v5
	v_fma_f32 v4, -v4, v7, v6
	v_div_fmas_f32 v4, v4, v5, v7
	v_div_fixup_f32 v1, v4, v1, 1.0
	v_mul_f32_e32 v0, v0, v1
	ds_write_b32 v140, v0 offset:17408
	s_waitcnt vmcnt(15)
	v_mov_b32_e32 v0, v198
	v_mul_f32_e32 v1, 0xbfb8aa3b, v0
	v_exp_f32_e32 v1, v1
	s_nop 0
	v_add_f32_e32 v1, 1.0, v1
	v_div_scale_f32 v4, s[72:73], v1, v1, 1.0
	v_rcp_f32_e32 v5, v4
	s_nop 0
	v_fma_f32 v6, -v4, v5, 1.0
	v_fmac_f32_e32 v5, v6, v5
	v_div_scale_f32 v6, vcc, 1.0, v1, 1.0
	v_mul_f32_e32 v7, v6, v5
	v_fma_f32 v10, -v4, v7, v6
	v_fmac_f32_e32 v7, v10, v5
	v_fma_f32 v4, -v4, v7, v6
	v_div_fmas_f32 v4, v4, v5, v7
	v_div_fixup_f32 v1, v4, v1, 1.0
	v_mul_f32_e32 v0, v0, v1
	ds_write_b32 v140, v0 offset:18432
	s_waitcnt vmcnt(14)
	v_mov_b32_e32 v0, v199
	v_mul_f32_e32 v1, 0xbfb8aa3b, v0
	v_exp_f32_e32 v1, v1
	s_nop 0
	v_add_f32_e32 v1, 1.0, v1
	v_div_scale_f32 v4, s[72:73], v1, v1, 1.0
	v_rcp_f32_e32 v5, v4
	s_nop 0
	v_fma_f32 v6, -v4, v5, 1.0
	v_fmac_f32_e32 v5, v6, v5
	v_div_scale_f32 v6, vcc, 1.0, v1, 1.0
	v_mul_f32_e32 v7, v6, v5
	v_fma_f32 v10, -v4, v7, v6
	v_fmac_f32_e32 v7, v10, v5
	v_fma_f32 v4, -v4, v7, v6
	v_div_fmas_f32 v4, v4, v5, v7
	v_div_fixup_f32 v1, v4, v1, 1.0
	v_mul_f32_e32 v0, v0, v1
	ds_write_b32 v140, v0 offset:19456
	s_waitcnt vmcnt(13)
	v_mov_b32_e32 v0, v200
	v_mul_f32_e32 v1, 0xbfb8aa3b, v0
	v_exp_f32_e32 v1, v1
	s_nop 0
	v_add_f32_e32 v1, 1.0, v1
	v_div_scale_f32 v4, s[72:73], v1, v1, 1.0
	v_rcp_f32_e32 v5, v4
	s_nop 0
	v_fma_f32 v6, -v4, v5, 1.0
	v_fmac_f32_e32 v5, v6, v5
	v_div_scale_f32 v6, vcc, 1.0, v1, 1.0
	v_mul_f32_e32 v7, v6, v5
	v_fma_f32 v10, -v4, v7, v6
	v_fmac_f32_e32 v7, v10, v5
	v_fma_f32 v4, -v4, v7, v6
	v_div_fmas_f32 v4, v4, v5, v7
	v_div_fixup_f32 v1, v4, v1, 1.0
	v_mul_f32_e32 v0, v0, v1
	ds_write_b32 v140, v0 offset:20480
	s_waitcnt vmcnt(12)
	v_mov_b32_e32 v0, v201
	v_mul_f32_e32 v1, 0xbfb8aa3b, v0
	v_exp_f32_e32 v1, v1
	s_nop 0
	v_add_f32_e32 v1, 1.0, v1
	v_div_scale_f32 v4, s[72:73], v1, v1, 1.0
	v_rcp_f32_e32 v5, v4
	s_nop 0
	v_fma_f32 v6, -v4, v5, 1.0
	v_fmac_f32_e32 v5, v6, v5
	v_div_scale_f32 v6, vcc, 1.0, v1, 1.0
	v_mul_f32_e32 v7, v6, v5
	v_fma_f32 v10, -v4, v7, v6
	v_fmac_f32_e32 v7, v10, v5
	v_fma_f32 v4, -v4, v7, v6
	v_div_fmas_f32 v4, v4, v5, v7
	v_div_fixup_f32 v1, v4, v1, 1.0
	v_mul_f32_e32 v0, v0, v1
	ds_write_b32 v140, v0 offset:21504
	s_waitcnt vmcnt(11)
	v_mov_b32_e32 v0, v202
	v_mul_f32_e32 v1, 0xbfb8aa3b, v0
	v_exp_f32_e32 v1, v1
	s_nop 0
	v_add_f32_e32 v1, 1.0, v1
	v_div_scale_f32 v4, s[72:73], v1, v1, 1.0
	v_rcp_f32_e32 v5, v4
	s_nop 0
	v_fma_f32 v6, -v4, v5, 1.0
	v_fmac_f32_e32 v5, v6, v5
	v_div_scale_f32 v6, vcc, 1.0, v1, 1.0
	v_mul_f32_e32 v7, v6, v5
	v_fma_f32 v10, -v4, v7, v6
	v_fmac_f32_e32 v7, v10, v5
	v_fma_f32 v4, -v4, v7, v6
	v_div_fmas_f32 v4, v4, v5, v7
	v_div_fixup_f32 v1, v4, v1, 1.0
	v_mul_f32_e32 v0, v0, v1
	ds_write_b32 v140, v0 offset:22528
	s_waitcnt vmcnt(10)
	v_mov_b32_e32 v0, v203
	v_mul_f32_e32 v1, 0xbfb8aa3b, v0
	v_exp_f32_e32 v1, v1
	s_nop 0
	v_add_f32_e32 v1, 1.0, v1
	v_div_scale_f32 v4, s[72:73], v1, v1, 1.0
	v_rcp_f32_e32 v5, v4
	s_nop 0
	v_fma_f32 v6, -v4, v5, 1.0
	v_fmac_f32_e32 v5, v6, v5
	v_div_scale_f32 v6, vcc, 1.0, v1, 1.0
	v_mul_f32_e32 v7, v6, v5
	v_fma_f32 v10, -v4, v7, v6
	v_fmac_f32_e32 v7, v10, v5
	v_fma_f32 v4, -v4, v7, v6
	v_div_fmas_f32 v4, v4, v5, v7
	v_div_fixup_f32 v1, v4, v1, 1.0
	v_mul_f32_e32 v0, v0, v1
	ds_write_b32 v140, v0 offset:23552
	s_waitcnt vmcnt(9)
	v_mov_b32_e32 v0, v204
	v_mul_f32_e32 v1, 0xbfb8aa3b, v0
	v_exp_f32_e32 v1, v1
	s_nop 0
	v_add_f32_e32 v1, 1.0, v1
	v_div_scale_f32 v4, s[72:73], v1, v1, 1.0
	v_rcp_f32_e32 v5, v4
	s_nop 0
	v_fma_f32 v6, -v4, v5, 1.0
	v_fmac_f32_e32 v5, v6, v5
	v_div_scale_f32 v6, vcc, 1.0, v1, 1.0
	v_mul_f32_e32 v7, v6, v5
	v_fma_f32 v10, -v4, v7, v6
	v_fmac_f32_e32 v7, v10, v5
	v_fma_f32 v4, -v4, v7, v6
	v_div_fmas_f32 v4, v4, v5, v7
	v_div_fixup_f32 v1, v4, v1, 1.0
	v_mul_f32_e32 v0, v0, v1
	ds_write_b32 v140, v0 offset:24576
	s_waitcnt vmcnt(8)
	v_mov_b32_e32 v0, v205
	v_mul_f32_e32 v1, 0xbfb8aa3b, v0
	v_exp_f32_e32 v1, v1
	s_nop 0
	v_add_f32_e32 v1, 1.0, v1
	v_div_scale_f32 v4, s[72:73], v1, v1, 1.0
	v_rcp_f32_e32 v5, v4
	s_nop 0
	v_fma_f32 v6, -v4, v5, 1.0
	v_fmac_f32_e32 v5, v6, v5
	v_div_scale_f32 v6, vcc, 1.0, v1, 1.0
	v_mul_f32_e32 v7, v6, v5
	v_fma_f32 v10, -v4, v7, v6
	v_fmac_f32_e32 v7, v10, v5
	v_fma_f32 v4, -v4, v7, v6
	v_div_fmas_f32 v4, v4, v5, v7
	v_div_fixup_f32 v1, v4, v1, 1.0
	v_mul_f32_e32 v0, v0, v1
	ds_write_b32 v140, v0 offset:25600
	s_waitcnt vmcnt(7)
	v_mov_b32_e32 v0, v206
	v_mul_f32_e32 v1, 0xbfb8aa3b, v0
	v_exp_f32_e32 v1, v1
	s_nop 0
	v_add_f32_e32 v1, 1.0, v1
	v_div_scale_f32 v4, s[72:73], v1, v1, 1.0
	v_rcp_f32_e32 v5, v4
	s_nop 0
	v_fma_f32 v6, -v4, v5, 1.0
	v_fmac_f32_e32 v5, v6, v5
	v_div_scale_f32 v6, vcc, 1.0, v1, 1.0
	v_mul_f32_e32 v7, v6, v5
	v_fma_f32 v10, -v4, v7, v6
	v_fmac_f32_e32 v7, v10, v5
	v_fma_f32 v4, -v4, v7, v6
	v_div_fmas_f32 v4, v4, v5, v7
	v_div_fixup_f32 v1, v4, v1, 1.0
	v_mul_f32_e32 v0, v0, v1
	ds_write_b32 v140, v0 offset:26624
	s_waitcnt vmcnt(6)
	v_mov_b32_e32 v0, v207
	v_mul_f32_e32 v1, 0xbfb8aa3b, v0
	v_exp_f32_e32 v1, v1
	s_nop 0
	v_add_f32_e32 v1, 1.0, v1
	v_div_scale_f32 v4, s[72:73], v1, v1, 1.0
	v_rcp_f32_e32 v5, v4
	s_nop 0
	v_fma_f32 v6, -v4, v5, 1.0
	v_fmac_f32_e32 v5, v6, v5
	v_div_scale_f32 v6, vcc, 1.0, v1, 1.0
	v_mul_f32_e32 v7, v6, v5
	v_fma_f32 v10, -v4, v7, v6
	v_fmac_f32_e32 v7, v10, v5
	v_fma_f32 v4, -v4, v7, v6
	v_div_fmas_f32 v4, v4, v5, v7
	v_div_fixup_f32 v1, v4, v1, 1.0
	v_mul_f32_e32 v0, v0, v1
	ds_write_b32 v140, v0 offset:27648
	s_waitcnt vmcnt(5)
	v_mov_b32_e32 v0, v208
	v_mul_f32_e32 v1, 0xbfb8aa3b, v0
	v_exp_f32_e32 v1, v1
	s_nop 0
	v_add_f32_e32 v1, 1.0, v1
	v_div_scale_f32 v4, s[72:73], v1, v1, 1.0
	v_rcp_f32_e32 v5, v4
	s_nop 0
	v_fma_f32 v6, -v4, v5, 1.0
	v_fmac_f32_e32 v5, v6, v5
	v_div_scale_f32 v6, vcc, 1.0, v1, 1.0
	v_mul_f32_e32 v7, v6, v5
	v_fma_f32 v10, -v4, v7, v6
	v_fmac_f32_e32 v7, v10, v5
	v_fma_f32 v4, -v4, v7, v6
	v_div_fmas_f32 v4, v4, v5, v7
	v_div_fixup_f32 v1, v4, v1, 1.0
	v_mul_f32_e32 v0, v0, v1
	ds_write_b32 v140, v0 offset:28672
	s_waitcnt vmcnt(4)
	v_mov_b32_e32 v0, v209
	v_mul_f32_e32 v1, 0xbfb8aa3b, v0
	v_exp_f32_e32 v1, v1
	s_nop 0
	v_add_f32_e32 v1, 1.0, v1
	v_div_scale_f32 v4, s[72:73], v1, v1, 1.0
	v_rcp_f32_e32 v5, v4
	s_nop 0
	v_fma_f32 v6, -v4, v5, 1.0
	v_fmac_f32_e32 v5, v6, v5
	v_div_scale_f32 v6, vcc, 1.0, v1, 1.0
	v_mul_f32_e32 v7, v6, v5
	v_fma_f32 v10, -v4, v7, v6
	v_fmac_f32_e32 v7, v10, v5
	v_fma_f32 v4, -v4, v7, v6
	v_div_fmas_f32 v4, v4, v5, v7
	v_div_fixup_f32 v1, v4, v1, 1.0
	v_mul_f32_e32 v0, v0, v1
	ds_write_b32 v140, v0 offset:29696
	s_waitcnt vmcnt(3)
	v_mov_b32_e32 v0, v210
	v_mul_f32_e32 v1, 0xbfb8aa3b, v0
	v_exp_f32_e32 v1, v1
	s_nop 0
	v_add_f32_e32 v1, 1.0, v1
	v_div_scale_f32 v4, s[72:73], v1, v1, 1.0
	v_rcp_f32_e32 v5, v4
	s_nop 0
	v_fma_f32 v6, -v4, v5, 1.0
	v_fmac_f32_e32 v5, v6, v5
	v_div_scale_f32 v6, vcc, 1.0, v1, 1.0
	v_mul_f32_e32 v7, v6, v5
	v_fma_f32 v10, -v4, v7, v6
	v_fmac_f32_e32 v7, v10, v5
	v_fma_f32 v4, -v4, v7, v6
	v_div_fmas_f32 v4, v4, v5, v7
	v_div_fixup_f32 v1, v4, v1, 1.0
	v_mul_f32_e32 v0, v0, v1
	ds_write_b32 v140, v0 offset:30720
	s_waitcnt vmcnt(2)
	v_mov_b32_e32 v0, v211
	v_mul_f32_e32 v1, 0xbfb8aa3b, v0
	v_exp_f32_e32 v1, v1
	s_nop 0
	v_add_f32_e32 v1, 1.0, v1
	v_div_scale_f32 v4, s[72:73], v1, v1, 1.0
	v_rcp_f32_e32 v5, v4
	s_nop 0
	v_fma_f32 v6, -v4, v5, 1.0
	v_fmac_f32_e32 v5, v6, v5
	v_div_scale_f32 v6, vcc, 1.0, v1, 1.0
	v_mul_f32_e32 v7, v6, v5
	v_fma_f32 v10, -v4, v7, v6
	v_fmac_f32_e32 v7, v10, v5
	v_fma_f32 v4, -v4, v7, v6
	v_div_fmas_f32 v4, v4, v5, v7
	v_div_fixup_f32 v1, v4, v1, 1.0
	v_mul_f32_e32 v0, v0, v1
	ds_write_b32 v140, v0 offset:31744
	s_waitcnt vmcnt(1)
	v_mov_b32_e32 v0, v212
	v_mul_f32_e32 v1, 0xbfb8aa3b, v0
	v_exp_f32_e32 v1, v1
	s_nop 0
	v_add_f32_e32 v1, 1.0, v1
	v_div_scale_f32 v4, s[72:73], v1, v1, 1.0
	v_rcp_f32_e32 v5, v4
	s_nop 0
	v_fma_f32 v6, -v4, v5, 1.0
	v_fmac_f32_e32 v5, v6, v5
	v_div_scale_f32 v6, vcc, 1.0, v1, 1.0
	v_mul_f32_e32 v7, v6, v5
	v_fma_f32 v10, -v4, v7, v6
	v_fmac_f32_e32 v7, v10, v5
	v_fma_f32 v4, -v4, v7, v6
	v_div_fmas_f32 v4, v4, v5, v7
	v_div_fixup_f32 v1, v4, v1, 1.0
	v_mul_f32_e32 v0, v0, v1
	ds_write_b32 v140, v0 offset:32768
	s_waitcnt vmcnt(0)
	v_mov_b32_e32 v0, v213
	v_mul_f32_e32 v1, 0xbfb8aa3b, v0
	v_exp_f32_e32 v1, v1
	s_nop 0
	v_add_f32_e32 v1, 1.0, v1
	v_div_scale_f32 v4, s[72:73], v1, v1, 1.0
	v_rcp_f32_e32 v5, v4
	s_nop 0
	v_fma_f32 v6, -v4, v5, 1.0
	v_fmac_f32_e32 v5, v6, v5
	v_div_scale_f32 v6, vcc, 1.0, v1, 1.0
	v_mul_f32_e32 v7, v6, v5
	v_fma_f32 v10, -v4, v7, v6
	v_fmac_f32_e32 v7, v10, v5
	v_fma_f32 v4, -v4, v7, v6
	v_div_fmas_f32 v4, v4, v5, v7
	v_div_fixup_f32 v1, v4, v1, 1.0
	v_mul_f32_e32 v0, v0, v1
	ds_write_b32 v140, v0 offset:33792
